# phase F K-loop: LDS-DMA pieces use scalar base + 32-bit lane offset (saddr form) instead of per-piece v_lshl_add_u64 64-bit addresses; stacked on the dwordx4-store version
# speedup vs baseline: 1.0209x; 1.0033x over previous
.LBB0_510:
	s_add_u32 s6, s56, 0xfff80080
	s_addc_u32 s7, s57, -1
	s_add_i32 s20, 0, 0x10000
	s_cmp_eq_u32 s23, 28
	s_cselect_b32 s61, s11, s7
	s_cselect_b32 s60, s18, s6
	v_add_u32_e32 v144, s20, v147
	s_cselect_b32 s59, s19, s22
	s_cselect_b32 s58, s12, s13
	s_add_i32 s6, 0, 0x14000
	ds_read_b128 v[140:143], v144
	ds_read_b128 v[152:155], v144 offset:1024
	ds_read_b128 v[156:159], v144 offset:2048
	ds_read_b128 v[160:163], v144 offset:3072
	v_add_u32_e32 v144, s6, v147
	ds_read_b128 v[164:167], v144
	ds_read_b128 v[168:171], v144 offset:1024
	ds_read_b128 v[172:175], v144 offset:2048
	ds_read_b128 v[176:179], v144 offset:3072
	s_add_i32 m0, s28, 0xc000
	ds_read_b128 v[180:183], v150
	ds_read_b128 v[184:187], v150 offset:1024
	ds_read_b128 v[188:191], v150 offset:2048
	ds_read_b128 v[200:203], v150 offset:3072
	ds_read_b128 v[204:207], v150 offset:4096
	ds_read_b128 v[214:217], v150 offset:5120
	ds_read_b128 v[218:221], v150 offset:6144
	ds_read_b128 v[222:225], v150 offset:7168
	global_load_lds_dwordx4 v136, s[56:57]
	s_add_i32 m0, s28, 0xe000
	s_nop 0
	global_load_lds_dwordx4 v138, s[56:57]
	s_waitcnt vmcnt(8)
	s_waitcnt lgkmcnt(0)
	s_barrier
	s_setprio 1
	s_waitcnt lgkmcnt(0)
	v_mfma_f32_16x16x32_bf16 v[126:129], v[140:143], v[180:183], v[126:129]
	v_mfma_f32_16x16x32_bf16 v[122:125], v[156:159], v[180:183], v[122:125]
	v_mfma_f32_16x16x32_bf16 v[110:113], v[140:143], v[188:191], v[110:113]
	v_mfma_f32_16x16x32_bf16 v[106:109], v[156:159], v[188:191], v[106:109]
	v_mfma_f32_16x16x32_bf16 v[94:97], v[140:143], v[204:207], v[94:97]
	v_mfma_f32_16x16x32_bf16 v[90:93], v[156:159], v[204:207], v[90:93]
	v_mfma_f32_16x16x32_bf16 v[78:81], v[140:143], v[218:221], v[78:81]
	v_mfma_f32_16x16x32_bf16 v[74:77], v[156:159], v[218:221], v[74:77]
	v_mfma_f32_16x16x32_bf16 v[126:129], v[152:155], v[184:187], v[126:129]
	v_mfma_f32_16x16x32_bf16 v[122:125], v[160:163], v[184:187], v[122:125]
	v_mfma_f32_16x16x32_bf16 v[110:113], v[152:155], v[200:203], v[110:113]
	v_mfma_f32_16x16x32_bf16 v[106:109], v[160:163], v[200:203], v[106:109]
	v_mfma_f32_16x16x32_bf16 v[94:97], v[152:155], v[214:217], v[94:97]
	v_mfma_f32_16x16x32_bf16 v[90:93], v[160:163], v[214:217], v[90:93]
	v_mfma_f32_16x16x32_bf16 v[78:81], v[152:155], v[222:225], v[78:81]
	v_mfma_f32_16x16x32_bf16 v[74:77], v[160:163], v[222:225], v[74:77]
	s_setprio 0
	s_setprio 1
	v_mfma_f32_16x16x32_bf16 v[118:121], v[164:167], v[180:183], v[118:121]
	v_mfma_f32_16x16x32_bf16 v[114:117], v[172:175], v[180:183], v[114:117]
	v_mfma_f32_16x16x32_bf16 v[102:105], v[164:167], v[188:191], v[102:105]
	v_mfma_f32_16x16x32_bf16 v[98:101], v[172:175], v[188:191], v[98:101]
	v_mfma_f32_16x16x32_bf16 v[86:89], v[164:167], v[204:207], v[86:89]
	v_mfma_f32_16x16x32_bf16 v[82:85], v[172:175], v[204:207], v[82:85]
	v_mfma_f32_16x16x32_bf16 v[70:73], v[164:167], v[218:221], v[70:73]
	v_mfma_f32_16x16x32_bf16 v[66:69], v[172:175], v[218:221], v[66:69]
	v_mfma_f32_16x16x32_bf16 v[118:121], v[168:171], v[184:187], v[118:121]
	v_mfma_f32_16x16x32_bf16 v[114:117], v[176:179], v[184:187], v[114:117]
	v_mfma_f32_16x16x32_bf16 v[102:105], v[168:171], v[200:203], v[102:105]
	v_mfma_f32_16x16x32_bf16 v[98:101], v[176:179], v[200:203], v[98:101]
	v_mfma_f32_16x16x32_bf16 v[86:89], v[168:171], v[214:217], v[86:89]
	v_mfma_f32_16x16x32_bf16 v[82:85], v[176:179], v[214:217], v[82:85]
	v_mfma_f32_16x16x32_bf16 v[70:73], v[168:171], v[222:225], v[70:73]
	v_mfma_f32_16x16x32_bf16 v[66:69], v[176:179], v[222:225], v[66:69]
	s_setprio 0
	s_barrier
	s_add_i32 s7, s20, s14
	s_mov_b32 m0, s7
	ds_read_b128 v[180:183], v150 offset:16384
	ds_read_b128 v[184:187], v150 offset:17408
	ds_read_b128 v[188:191], v150 offset:18432
	ds_read_b128 v[200:203], v150 offset:19456
	ds_read_b128 v[204:207], v150 offset:20480
	ds_read_b128 v[214:217], v150 offset:21504
	ds_read_b128 v[218:221], v150 offset:22528
	ds_read_b128 v[222:225], v150 offset:23552
	global_load_lds_dwordx4 v0, s[58:59]
	s_add_i32 m0, s7, 0x2000
	s_add_u32 s20, s58, 0x80000
	s_addc_u32 s21, s59, 0
	s_add_i32 s6, s6, s14
	global_load_lds_dwordx4 v130, s[58:59]
	s_mov_b32 m0, s6
	s_nop 0
	global_load_lds_dwordx4 v0, s[20:21]
	s_add_i32 m0, s6, 0x2000
	s_nop 0
	global_load_lds_dwordx4 v130, s[20:21]
	s_mov_b32 m0, s28
	s_nop 0
	global_load_lds_dwordx4 v134, s[60:61]
	s_mov_b32 m0, s29
	s_nop 0
	global_load_lds_dwordx4 v132, s[60:61]
	s_waitcnt vmcnt(8)
	s_waitcnt lgkmcnt(0)
	s_barrier
	s_setprio 1
	s_waitcnt lgkmcnt(0)
	v_mfma_f32_16x16x32_bf16 v[62:65], v[140:143], v[180:183], v[62:65]
	v_mfma_f32_16x16x32_bf16 v[58:61], v[156:159], v[180:183], v[58:61]
	v_mfma_f32_16x16x32_bf16 v[46:49], v[140:143], v[188:191], v[46:49]
	v_mfma_f32_16x16x32_bf16 v[42:45], v[156:159], v[188:191], v[42:45]
	v_mfma_f32_16x16x32_bf16 v[30:33], v[140:143], v[204:207], v[30:33]
	v_mfma_f32_16x16x32_bf16 v[26:29], v[156:159], v[204:207], v[26:29]
	v_mfma_f32_16x16x32_bf16 v[14:17], v[140:143], v[218:221], v[14:17]
	v_mfma_f32_16x16x32_bf16 v[10:13], v[156:159], v[218:221], v[10:13]
	v_mfma_f32_16x16x32_bf16 v[62:65], v[152:155], v[184:187], v[62:65]
	v_mfma_f32_16x16x32_bf16 v[58:61], v[160:163], v[184:187], v[58:61]
	v_mfma_f32_16x16x32_bf16 v[46:49], v[152:155], v[200:203], v[46:49]
	v_mfma_f32_16x16x32_bf16 v[42:45], v[160:163], v[200:203], v[42:45]
	v_mfma_f32_16x16x32_bf16 v[30:33], v[152:155], v[214:217], v[30:33]
	v_mfma_f32_16x16x32_bf16 v[26:29], v[160:163], v[214:217], v[26:29]
	v_mfma_f32_16x16x32_bf16 v[14:17], v[152:155], v[222:225], v[14:17]
	v_mfma_f32_16x16x32_bf16 v[10:13], v[160:163], v[222:225], v[10:13]
	s_setprio 0
	s_setprio 1
	v_mfma_f32_16x16x32_bf16 v[54:57], v[164:167], v[180:183], v[54:57]
	v_mfma_f32_16x16x32_bf16 v[50:53], v[172:175], v[180:183], v[50:53]
	v_mfma_f32_16x16x32_bf16 v[38:41], v[164:167], v[188:191], v[38:41]
	v_mfma_f32_16x16x32_bf16 v[34:37], v[172:175], v[188:191], v[34:37]
	v_mfma_f32_16x16x32_bf16 v[22:25], v[164:167], v[204:207], v[22:25]
	v_mfma_f32_16x16x32_bf16 v[18:21], v[172:175], v[204:207], v[18:21]
	v_mfma_f32_16x16x32_bf16 v[6:9], v[164:167], v[218:221], v[6:9]
	v_mfma_f32_16x16x32_bf16 v[2:5], v[172:175], v[218:221], v[2:5]
	v_mfma_f32_16x16x32_bf16 v[54:57], v[168:171], v[184:187], v[54:57]
	v_mfma_f32_16x16x32_bf16 v[50:53], v[176:179], v[184:187], v[50:53]
	v_mfma_f32_16x16x32_bf16 v[38:41], v[168:171], v[200:203], v[38:41]
	v_mfma_f32_16x16x32_bf16 v[34:37], v[176:179], v[200:203], v[34:37]
	v_mfma_f32_16x16x32_bf16 v[22:25], v[168:171], v[214:217], v[22:25]
	v_mfma_f32_16x16x32_bf16 v[18:21], v[176:179], v[214:217], v[18:21]
	v_mfma_f32_16x16x32_bf16 v[6:9], v[168:171], v[222:225], v[6:9]
	v_mfma_f32_16x16x32_bf16 v[2:5], v[176:179], v[222:225], v[2:5]
	s_setprio 0
	s_barrier
	s_add_i32 s6, 0, 0x18000
	v_add_u32_e32 v151, s6, v147
	s_add_i32 s7, 0, 0x1c000
	ds_read_b128 v[140:143], v151
	ds_read_b128 v[152:155], v151 offset:1024
	ds_read_b128 v[156:159], v151 offset:2048
	ds_read_b128 v[160:163], v151 offset:3072
	v_add_u32_e32 v151, s7, v147
	ds_read_b128 v[164:167], v151
	ds_read_b128 v[168:171], v151 offset:1024
	ds_read_b128 v[172:175], v151 offset:2048
	ds_read_b128 v[176:179], v151 offset:3072
	s_add_u32 s20, s60, 0x80000
	s_addc_u32 s21, s61, 0
	s_mov_b32 m0, s30
	ds_read_b128 v[180:183], v150 offset:32768
	ds_read_b128 v[184:187], v150 offset:33792
	ds_read_b128 v[188:191], v150 offset:34816
	ds_read_b128 v[200:203], v150 offset:35840
	ds_read_b128 v[204:207], v150 offset:36864
	ds_read_b128 v[214:217], v150 offset:37888
	ds_read_b128 v[218:221], v150 offset:38912
	ds_read_b128 v[222:225], v150 offset:39936
	global_load_lds_dwordx4 v134, s[20:21]
	s_mov_b32 m0, s31
	s_nop 0
	global_load_lds_dwordx4 v132, s[20:21]
	s_waitcnt vmcnt(8)
	s_waitcnt lgkmcnt(0)
	s_barrier
	s_setprio 1
	s_waitcnt lgkmcnt(0)
	v_mfma_f32_16x16x32_bf16 v[126:129], v[140:143], v[180:183], v[126:129]
	v_mfma_f32_16x16x32_bf16 v[122:125], v[156:159], v[180:183], v[122:125]
	v_mfma_f32_16x16x32_bf16 v[110:113], v[140:143], v[188:191], v[110:113]
	v_mfma_f32_16x16x32_bf16 v[106:109], v[156:159], v[188:191], v[106:109]
	v_mfma_f32_16x16x32_bf16 v[94:97], v[140:143], v[204:207], v[94:97]
	v_mfma_f32_16x16x32_bf16 v[90:93], v[156:159], v[204:207], v[90:93]
	v_mfma_f32_16x16x32_bf16 v[78:81], v[140:143], v[218:221], v[78:81]
	v_mfma_f32_16x16x32_bf16 v[74:77], v[156:159], v[218:221], v[74:77]
	v_mfma_f32_16x16x32_bf16 v[126:129], v[152:155], v[184:187], v[126:129]
	v_mfma_f32_16x16x32_bf16 v[122:125], v[160:163], v[184:187], v[122:125]
	v_mfma_f32_16x16x32_bf16 v[110:113], v[152:155], v[200:203], v[110:113]
	v_mfma_f32_16x16x32_bf16 v[106:109], v[160:163], v[200:203], v[106:109]
	v_mfma_f32_16x16x32_bf16 v[94:97], v[152:155], v[214:217], v[94:97]
	v_mfma_f32_16x16x32_bf16 v[90:93], v[160:163], v[214:217], v[90:93]
	v_mfma_f32_16x16x32_bf16 v[78:81], v[152:155], v[222:225], v[78:81]
	v_mfma_f32_16x16x32_bf16 v[74:77], v[160:163], v[222:225], v[74:77]
	s_setprio 0
	s_setprio 1
	v_mfma_f32_16x16x32_bf16 v[118:121], v[164:167], v[180:183], v[118:121]
	v_mfma_f32_16x16x32_bf16 v[114:117], v[172:175], v[180:183], v[114:117]
	v_mfma_f32_16x16x32_bf16 v[102:105], v[164:167], v[188:191], v[102:105]
	v_mfma_f32_16x16x32_bf16 v[98:101], v[172:175], v[188:191], v[98:101]
	v_mfma_f32_16x16x32_bf16 v[86:89], v[164:167], v[204:207], v[86:89]
	v_mfma_f32_16x16x32_bf16 v[82:85], v[172:175], v[204:207], v[82:85]
	v_mfma_f32_16x16x32_bf16 v[70:73], v[164:167], v[218:221], v[70:73]
	v_mfma_f32_16x16x32_bf16 v[66:69], v[172:175], v[218:221], v[66:69]
	v_mfma_f32_16x16x32_bf16 v[118:121], v[168:171], v[184:187], v[118:121]
	v_mfma_f32_16x16x32_bf16 v[114:117], v[176:179], v[184:187], v[114:117]
	v_mfma_f32_16x16x32_bf16 v[102:105], v[168:171], v[200:203], v[102:105]
	v_mfma_f32_16x16x32_bf16 v[98:101], v[176:179], v[200:203], v[98:101]
	v_mfma_f32_16x16x32_bf16 v[86:89], v[168:171], v[214:217], v[86:89]
	v_mfma_f32_16x16x32_bf16 v[82:85], v[176:179], v[214:217], v[82:85]
	v_mfma_f32_16x16x32_bf16 v[70:73], v[168:171], v[222:225], v[70:73]
	v_mfma_f32_16x16x32_bf16 v[66:69], v[176:179], v[222:225], v[66:69]
	s_setprio 0
	s_barrier
	s_add_i32 s6, s6, s14
	s_add_u32 s100, s58, s72
	s_addc_u32 s101, s59, s73
	s_mov_b32 m0, s6
	ds_read_b128 v[180:183], v150 offset:49152
	ds_read_b128 v[184:187], v150 offset:50176
	ds_read_b128 v[188:191], v150 offset:51200
	ds_read_b128 v[200:203], v150 offset:52224
	ds_read_b128 v[204:207], v150 offset:53248
	ds_read_b128 v[214:217], v150 offset:54272
	ds_read_b128 v[218:221], v150 offset:55296
	ds_read_b128 v[222:225], v150 offset:56320
	global_load_lds_dwordx4 v0, s[100:101]
	s_add_i32 m0, s6, 0x2000
	s_add_u32 s20, s58, 0x80080
	s_addc_u32 s21, s59, 0
	s_add_i32 s6, s7, s14
	global_load_lds_dwordx4 v130, s[100:101]
	s_add_u32 s100, s60, s72
	s_addc_u32 s101, s61, s73
	s_mov_b32 m0, s6
	s_nop 0
	global_load_lds_dwordx4 v0, s[20:21]
	s_add_i32 m0, s6, 0x2000
	s_nop 0
	global_load_lds_dwordx4 v130, s[20:21]
	s_mov_b32 m0, s62
	s_nop 0
	global_load_lds_dwordx4 v134, s[100:101]
	s_mov_b32 m0, s63
	s_nop 0
	global_load_lds_dwordx4 v132, s[100:101]
	s_waitcnt vmcnt(8)
	s_waitcnt lgkmcnt(0)
	s_barrier
	s_setprio 1
	s_waitcnt lgkmcnt(0)
	v_mfma_f32_16x16x32_bf16 v[62:65], v[140:143], v[180:183], v[62:65]
	v_mfma_f32_16x16x32_bf16 v[58:61], v[156:159], v[180:183], v[58:61]
	v_mfma_f32_16x16x32_bf16 v[46:49], v[140:143], v[188:191], v[46:49]
	v_mfma_f32_16x16x32_bf16 v[42:45], v[156:159], v[188:191], v[42:45]
	v_mfma_f32_16x16x32_bf16 v[30:33], v[140:143], v[204:207], v[30:33]
	v_mfma_f32_16x16x32_bf16 v[26:29], v[156:159], v[204:207], v[26:29]
	v_mfma_f32_16x16x32_bf16 v[14:17], v[140:143], v[218:221], v[14:17]
	v_mfma_f32_16x16x32_bf16 v[10:13], v[156:159], v[218:221], v[10:13]
	v_mfma_f32_16x16x32_bf16 v[62:65], v[152:155], v[184:187], v[62:65]
	v_mfma_f32_16x16x32_bf16 v[58:61], v[160:163], v[184:187], v[58:61]
	v_mfma_f32_16x16x32_bf16 v[46:49], v[152:155], v[200:203], v[46:49]
	v_mfma_f32_16x16x32_bf16 v[42:45], v[160:163], v[200:203], v[42:45]
	v_mfma_f32_16x16x32_bf16 v[30:33], v[152:155], v[214:217], v[30:33]
	v_mfma_f32_16x16x32_bf16 v[26:29], v[160:163], v[214:217], v[26:29]
	v_mfma_f32_16x16x32_bf16 v[14:17], v[152:155], v[222:225], v[14:17]
	v_mfma_f32_16x16x32_bf16 v[10:13], v[160:163], v[222:225], v[10:13]
	s_setprio 0
	s_setprio 1
	v_mfma_f32_16x16x32_bf16 v[54:57], v[164:167], v[180:183], v[54:57]
	v_mfma_f32_16x16x32_bf16 v[50:53], v[172:175], v[180:183], v[50:53]
	v_mfma_f32_16x16x32_bf16 v[38:41], v[164:167], v[188:191], v[38:41]
	v_mfma_f32_16x16x32_bf16 v[34:37], v[172:175], v[188:191], v[34:37]
	v_mfma_f32_16x16x32_bf16 v[22:25], v[164:167], v[204:207], v[22:25]
	v_mfma_f32_16x16x32_bf16 v[18:21], v[172:175], v[204:207], v[18:21]
	v_mfma_f32_16x16x32_bf16 v[6:9], v[164:167], v[218:221], v[6:9]
	v_mfma_f32_16x16x32_bf16 v[2:5], v[172:175], v[218:221], v[2:5]
	v_mfma_f32_16x16x32_bf16 v[54:57], v[168:171], v[184:187], v[54:57]
	v_mfma_f32_16x16x32_bf16 v[50:53], v[176:179], v[184:187], v[50:53]
	v_mfma_f32_16x16x32_bf16 v[38:41], v[168:171], v[200:203], v[38:41]
	v_mfma_f32_16x16x32_bf16 v[34:37], v[176:179], v[200:203], v[34:37]
	v_mfma_f32_16x16x32_bf16 v[22:25], v[168:171], v[214:217], v[22:25]
	v_mfma_f32_16x16x32_bf16 v[18:21], v[176:179], v[214:217], v[18:21]
	v_mfma_f32_16x16x32_bf16 v[6:9], v[168:171], v[222:225], v[6:9]
	v_mfma_f32_16x16x32_bf16 v[2:5], v[176:179], v[222:225], v[2:5]
	s_setprio 0
	s_barrier
	s_add_i32 s23, s23, 2
	s_add_u32 s56, s56, 0x100
	s_addc_u32 s57, s57, 0
	s_add_u32 s13, s13, 0x100
	s_addc_u32 s22, s22, 0
	s_cmp_gt_u32 s23, 29
	s_cbranch_scc0 .LBB0_510
	s_and_b64 vcc, exec, s[44:45]
	s_cbranch_vccz .LBB0_513
	s_barrier
